# speedup vs baseline: 1.0180x; 1.0014x over previous
; __device__ __forceinline__ int crow(int r, int hi) { return (r & 3) + 8 * (r >> 2) + 4 * hi; }
; __device__ __forceinline__ void partialSM(f32x16& p0, f32x16& p1, float& m_reg, float& mn, float& alpha) {
;   constexpr float C = SCALE * 1.4426950408889634f;
;   float pmax = p0[0];
; #pragma unroll
;   for (int r = 1; r < 16; ++r) pmax = fmaxf(pmax, p0[r]);
; #pragma unroll
;   for (int r = 0; r < 16; ++r) pmax = fmaxf(pmax, p1[r]);
;   { auto rr = __builtin_amdgcn_permlane32_swap(__float_as_uint(pmax), __float_as_uint(pmax), false, false);
;     pmax = fmaxf(__uint_as_float(rr[0]), __uint_as_float(rr[1])); }
;   if (__builtin_expect(__all(pmax - m_reg <= THR / SCALE), 1)) { mn = m_reg; alpha = 1.f; }
;   else { mn = fmaxf(m_reg, pmax); alpha = __builtin_amdgcn_exp2f((m_reg - mn) * C); m_reg = mn; }
; __device__ __forceinline__ void na_items(const Params& p, int l, int L, char* shm, const int tid, const int local, const int G, const int nNA) {
;     ...
;         for (int d0 = 0; d0 < 4; ++d0) {
;           bf16x8 b0 = *(const bf16x8*)(Kc + roff[d0]);
;           bf16x8 b1 = *(const bf16x8*)(Kc + roff[d0] + 4096);
;           p0 = __builtin_amdgcn_mfma_f32_32x32x16_bf16(b0, qr[d0], p0, 0, 0, 0);
;           p1 = __builtin_amdgcn_mfma_f32_32x32x16_bf16(b1, qr[d0], p1, 0, 0, 0);
;         }
;         {
;           const float* rb = rpbL + (kr - rq + 7) * 31 + (15 - qc);
; #pragma unroll
;           for (int r = 0; r < 16; ++r) {
;             const int kc = crow(r, hi);
;             const bool v0 = (kc >= c0) && (kc < c0 + 16);
;             const float b0 = rb[v0 ? kc : qc];
;             p0[r] = v0 ? p0[r] + b0 : -1e30f;
;             const int kc1 = kc + 32;
;             const bool v1 = (kc1 >= c0) && (kc1 < c0 + 16);
;             const float b1 = rb[v1 ? kc1 : qc];
;             p1[r] = v1 ? p1[r] + b1 : -1e30f;
;           }
;         }
;         float mn, alpha;
;         partialSM(p0, p1, m_reg, mn, alpha);
;         if (__any(alpha < 1.f)) {
;           if (hi == 0) wsf[r32] = alpha;
;           asm volatile("s_waitcnt lgkmcnt(0)" ::: "memory");
; #pragma unroll
;           for (int r = 0; r < 16; ++r) { const float a = wsf[crow(r, hi)]; o0[r] *= a; o1[r] *= a; }
;         }
.LBB0_447:
	s_and_b32 s97, s42, 1
	s_add_i32 s6, s99, s42
	s_cmp_ge_i32 s6, s46
	s_cselect_b64 s[42:43], -1, 0
	s_cmp_lt_i32 s6, s98
	s_cselect_b64 vcc, -1, 0
	s_and_b64 s[42:43], s[42:43], vcc
	s_andn2_b64 vcc, exec, s[42:43]
	s_cbranch_vccnz .LBB0_517
	s_lshl_b32 s6, s97, 13
	v_add_u32_e32 v236, s6, v109
	v_add_u32_e32 v237, s6, v120
	v_add_u32_e32 v240, s6, v121
	v_add_u32_e32 v241, s6, v122
	s_cmp_eq_u64 s[40:41], 0
	s_cbranch_scc1 .Lna_left
	ds_read_b128 v[220:223], v236
	ds_read_b128 v[224:227], v236 offset:4096
	ds_read_b128 v[228:231], v237
	ds_read_b128 v[232:235], v237 offset:4096
	ds_read2_b32 v[212:213], v117 offset0:24 offset1:25
	ds_read2_b32 v[214:215], v117 offset0:26 offset1:27
	ds_read2_b32 v[2:3], v117 offset0:32 offset1:33
	ds_read2_b32 v[4:5], v117 offset0:34 offset1:35
	ds_read2_b32 v[6:7], v117 offset0:40 offset1:41
	ds_read2_b32 v[8:9], v117 offset0:42 offset1:43
	ds_read2_b32 v[10:11], v117 offset0:48 offset1:49
	ds_read2_b32 v[12:13], v117 offset0:50 offset1:51
	ds_read2_b32 v[250:251], v117 offset0:56 offset1:57
	ds_read2_b32 v[252:253], v117 offset0:58 offset1:59
	v_mov_b32_e32 v244, 0xf149f2ca
	s_waitcnt lgkmcnt(13)
	v_mfma_f32_32x32x16_bf16 v[64:79], v[220:223], v[80:83], 0
	ds_read_b128 v[220:223], v240
	s_waitcnt lgkmcnt(13)
	v_mfma_f32_32x32x16_bf16 v[48:63], v[224:227], v[80:83], 0
	ds_read_b128 v[224:227], v240 offset:4096
	s_waitcnt lgkmcnt(13)
	v_mfma_f32_32x32x16_bf16 v[64:79], v[228:231], v[84:87], v[64:79]
	ds_read_b128 v[228:231], v241
	s_waitcnt lgkmcnt(13)
	v_mfma_f32_32x32x16_bf16 v[48:63], v[232:235], v[84:87], v[48:63]
	ds_read_b128 v[232:235], v241 offset:4096
	s_waitcnt lgkmcnt(3)
	v_mfma_f32_32x32x16_bf16 v[64:79], v[220:223], v[88:91], v[64:79]
	s_waitcnt lgkmcnt(2)
	v_mfma_f32_32x32x16_bf16 v[48:63], v[224:227], v[88:91], v[48:63]
	s_waitcnt lgkmcnt(1)
	v_mfma_f32_32x32x16_bf16 v[64:79], v[228:231], v[92:95], v[64:79]
	s_waitcnt lgkmcnt(0)
	v_mfma_f32_32x32x16_bf16 v[48:63], v[232:235], v[92:95], v[48:63]
	s_nop 9
	v_add_f32_e32 v76, v76, v212
	v_add_f32_e32 v77, v77, v213
	v_add_f32_e32 v78, v78, v214
	v_add_f32_e32 v79, v79, v215
	v_cndmask_b32_e64 v76, v244, v76, s[78:79]
	v_cndmask_b32_e64 v77, v244, v77, s[0:1]
	v_cndmask_b32_e64 v78, v244, v78, s[70:71]
	v_cndmask_b32_e64 v79, v244, v79, s[2:3]
	v_add_f32_e32 v48, v48, v2
	v_add_f32_e32 v49, v49, v3
	v_add_f32_e32 v50, v50, v4
	v_add_f32_e32 v51, v51, v5
	v_add_f32_e32 v52, v52, v6
	v_add_f32_e32 v53, v53, v7
	v_add_f32_e32 v54, v54, v8
	v_add_f32_e32 v55, v55, v9
	v_add_f32_e32 v56, v56, v10
	v_add_f32_e32 v57, v57, v11
	v_add_f32_e32 v58, v58, v12
	v_add_f32_e32 v59, v59, v13
	v_add_f32_e32 v60, v60, v250
	v_add_f32_e32 v61, v61, v251
	v_add_f32_e32 v62, v62, v252
	v_add_f32_e32 v63, v63, v253
	ds_read_b128 v[2:5], v237 offset:16384
	ds_read_b128 v[6:9], v237 offset:20480
	ds_read_b128 v[10:13], v240 offset:16384
	ds_read_b128 v[250:253], v240 offset:20480
	v_cndmask_b32_e64 v48, v244, v48, s[90:91]
	v_cndmask_b32_e64 v49, v244, v49, s[94:95]
	v_cndmask_b32_e64 v50, v244, v50, s[44:45]
	v_cndmask_b32_e64 v51, v244, v51, s[84:85]
	v_cndmask_b32_e64 v52, v244, v52, s[86:87]
	v_cndmask_b32_e64 v53, v244, v53, s[56:57]
	v_cndmask_b32_e64 v54, v244, v54, s[62:63]
	v_cndmask_b32_e64 v55, v244, v55, s[64:65]
	v_cndmask_b32_e64 v56, v244, v56, s[24:25]
	v_cndmask_b32_e64 v57, v244, v57, s[26:27]
	v_cndmask_b32_e64 v58, v244, v58, s[28:29]
	v_cndmask_b32_e64 v59, v244, v59, s[30:31]
	v_cndmask_b32_e64 v60, v244, v60, s[34:35]
	v_cndmask_b32_e64 v61, v244, v61, s[36:37]
	v_cndmask_b32_e64 v62, v244, v62, s[38:39]
	v_cndmask_b32_e64 v63, v244, v63, s[40:41]
	v_max3_f32 v245, v76, v77, v78
	v_max3_f32 v245, v245, v79, v48
	v_max3_f32 v245, v245, v49, v50
	v_max3_f32 v245, v245, v51, v52
	v_max3_f32 v245, v245, v53, v54
	v_max3_f32 v245, v245, v55, v56
	v_max3_f32 v245, v245, v57, v58
	v_max3_f32 v245, v245, v59, v60
	v_max3_f32 v245, v245, v61, v62
	v_max_f32_e32 v245, v245, v63
	v_mov_b32_e32 v238, v245
	s_nop 1
	v_permlane32_swap_b32_e32 v245, v238
	v_max_f32_e32 v245, v245, v238
	v_sub_f32_e32 v238, v245, v210
	s_mov_b32 s6, 0x42800000
	v_cmp_ge_f32_e32 vcc, s6, v238
	v_max_f32_e32 v238, v210, v245
	v_sub_f32_e32 v243, v210, v238
	v_mul_f32_e32 v243, 0x3e38aa3b, v243
	v_exp_f32_e32 v243, v243
	s_cmp_eq_u64 vcc, exec
	s_cselect_b64 s[42:43], -1, 0
	v_cndmask_b32_e64 v243, v243, 1.0, s[42:43]
	v_cmp_gt_f32_e32 vcc, 1.0, v243
	s_cbranch_vccz .Lna_norescale_R
	s_and_saveexec_b64 vcc, s[4:5]
	ds_write_b32 v170, v243 offset:32768
	s_or_b64 exec, exec, vcc
	s_waitcnt lgkmcnt(0)
	v_add_u32_e32 v0, s82, v108
	ds_read_b128 v[220:223], v0 offset:32864
	ds_read_b128 v[224:227], v0 offset:32832
	ds_read_b128 v[228:231], v0 offset:32800
	ds_read_b128 v[232:235], v0 offset:32768
	s_waitcnt lgkmcnt(0)
	v_pk_mul_f32 v[28:29], v[28:29], v[220:221]
	v_pk_mul_f32 v[30:31], v[30:31], v[222:223]
	v_pk_mul_f32 v[24:25], v[24:25], v[224:225]
	v_pk_mul_f32 v[26:27], v[26:27], v[226:227]
	v_pk_mul_f32 v[20:21], v[20:21], v[228:229]
	v_pk_mul_f32 v[22:23], v[22:23], v[230:231]
	v_pk_mul_f32 v[16:17], v[16:17], v[232:233]
	v_pk_mul_f32 v[18:19], v[18:19], v[234:235]
	v_pk_mul_f32 v[44:45], v[44:45], v[220:221]
	v_pk_mul_f32 v[46:47], v[46:47], v[222:223]
	v_pk_mul_f32 v[40:41], v[40:41], v[224:225]
	v_pk_mul_f32 v[42:43], v[42:43], v[226:227]
	v_pk_mul_f32 v[36:37], v[36:37], v[228:229]
	v_pk_mul_f32 v[38:39], v[38:39], v[230:231]
	v_pk_mul_f32 v[32:33], v[32:33], v[232:233]
	v_pk_mul_f32 v[34:35], v[34:35], v[234:235]

; __device__ __forceinline__ int crow(int r, int hi) { return (r & 3) + 8 * (r >> 2) + 4 * hi; }
; __device__ __forceinline__ void partialSM(f32x16& p0, f32x16& p1, float& m_reg, float& mn, float& alpha) {
;   constexpr float C = SCALE * 1.4426950408889634f;
;   float pmax = p0[0];
; #pragma unroll
;   for (int r = 1; r < 16; ++r) pmax = fmaxf(pmax, p0[r]);
; #pragma unroll
;   for (int r = 0; r < 16; ++r) pmax = fmaxf(pmax, p1[r]);
;   { auto rr = __builtin_amdgcn_permlane32_swap(__float_as_uint(pmax), __float_as_uint(pmax), false, false);
;     pmax = fmaxf(__uint_as_float(rr[0]), __uint_as_float(rr[1])); }
;   if (__builtin_expect(__all(pmax - m_reg <= THR / SCALE), 1)) { mn = m_reg; alpha = 1.f; }
;   else { mn = fmaxf(m_reg, pmax); alpha = __builtin_amdgcn_exp2f((m_reg - mn) * C); m_reg = mn; }
; __device__ __forceinline__ void na_items(const Params& p, int l, int L, char* shm, const int tid, const int local, const int G, const int nNA) {
;     ...
;         for (int d0 = 0; d0 < 4; ++d0) {
;           bf16x8 b0 = *(const bf16x8*)(Kc + roff[d0]);
;           bf16x8 b1 = *(const bf16x8*)(Kc + roff[d0] + 4096);
;           p0 = __builtin_amdgcn_mfma_f32_32x32x16_bf16(b0, qr[d0], p0, 0, 0, 0);
;           p1 = __builtin_amdgcn_mfma_f32_32x32x16_bf16(b1, qr[d0], p1, 0, 0, 0);
;         }
;         {
;           const float* rb = rpbL + (kr - rq + 7) * 31 + (15 - qc);
; #pragma unroll
;           for (int r = 0; r < 16; ++r) {
;             const int kc = crow(r, hi);
;             const bool v0 = (kc >= c0) && (kc < c0 + 16);
;             const float b0 = rb[v0 ? kc : qc];
;             p0[r] = v0 ? p0[r] + b0 : -1e30f;
;             const int kc1 = kc + 32;
;             const bool v1 = (kc1 >= c0) && (kc1 < c0 + 16);
;             const float b1 = rb[v1 ? kc1 : qc];
;             p1[r] = v1 ? p1[r] + b1 : -1e30f;
;           }
;         }
;         float mn, alpha;
;         partialSM(p0, p1, m_reg, mn, alpha);
;         if (__any(alpha < 1.f)) {
;           if (hi == 0) wsf[r32] = alpha;
;           asm volatile("s_waitcnt lgkmcnt(0)" ::: "memory");
; #pragma unroll
;           for (int r = 0; r < 16; ++r) { const float a = wsf[crow(r, hi)]; o0[r] *= a; o1[r] *= a; }
;         }
.Lna_left:
	ds_read_b128 v[220:223], v236
	ds_read_b128 v[224:227], v236 offset:4096
	ds_read_b128 v[228:231], v237
	ds_read_b128 v[232:235], v237 offset:4096
	ds_read2_b32 v[2:3], v117 offset1:1
	ds_read2_b32 v[4:5], v117 offset0:2 offset1:3
	ds_read2_b32 v[6:7], v117 offset0:8 offset1:9
	ds_read2_b32 v[8:9], v117 offset0:10 offset1:11
	ds_read2_b32 v[10:11], v117 offset0:16 offset1:17
	ds_read2_b32 v[12:13], v117 offset0:18 offset1:19
	ds_read2_b32 v[250:251], v117 offset0:24 offset1:25
	ds_read2_b32 v[252:253], v117 offset0:26 offset1:27
	ds_read2_b32 v[216:217], v117 offset0:32 offset1:33
	ds_read2_b32 v[218:219], v117 offset0:34 offset1:35
	v_mov_b32_e32 v244, 0xf149f2ca
	s_waitcnt lgkmcnt(13)
	v_mfma_f32_32x32x16_bf16 v[64:79], v[220:223], v[80:83], 0
	ds_read_b128 v[220:223], v240
	s_waitcnt lgkmcnt(13)
	v_mfma_f32_32x32x16_bf16 v[48:63], v[224:227], v[80:83], 0
	ds_read_b128 v[224:227], v240 offset:4096
	s_waitcnt lgkmcnt(13)
	v_mfma_f32_32x32x16_bf16 v[64:79], v[228:231], v[84:87], v[64:79]
	ds_read_b128 v[228:231], v241
	s_waitcnt lgkmcnt(13)
	v_mfma_f32_32x32x16_bf16 v[48:63], v[232:235], v[84:87], v[48:63]
	ds_read_b128 v[232:235], v241 offset:4096
	s_waitcnt lgkmcnt(3)
	v_mfma_f32_32x32x16_bf16 v[64:79], v[220:223], v[88:91], v[64:79]
	s_waitcnt lgkmcnt(2)
	v_mfma_f32_32x32x16_bf16 v[48:63], v[224:227], v[88:91], v[48:63]
	s_waitcnt lgkmcnt(1)
	v_mfma_f32_32x32x16_bf16 v[64:79], v[228:231], v[92:95], v[64:79]
	s_waitcnt lgkmcnt(0)
	v_mfma_f32_32x32x16_bf16 v[48:63], v[232:235], v[92:95], v[48:63]
	s_nop 9
	v_add_f32_e32 v64, v64, v2
	v_add_f32_e32 v65, v65, v3
	v_add_f32_e32 v66, v66, v4
	v_add_f32_e32 v67, v67, v5
	v_add_f32_e32 v68, v68, v6
	v_add_f32_e32 v69, v69, v7
	v_add_f32_e32 v70, v70, v8
	v_add_f32_e32 v71, v71, v9
	v_add_f32_e32 v72, v72, v10
	v_add_f32_e32 v73, v73, v11
	v_add_f32_e32 v74, v74, v12
	v_add_f32_e32 v75, v75, v13
	v_add_f32_e32 v76, v76, v250
	v_add_f32_e32 v77, v77, v251
	v_add_f32_e32 v78, v78, v252
	v_add_f32_e32 v79, v79, v253
	v_cndmask_b32_e64 v64, v244, v64, s[8:9]
	v_cndmask_b32_e64 v65, v244, v65, s[10:11]
	v_cndmask_b32_e64 v66, v244, v66, s[12:13]
	v_cndmask_b32_e64 v67, v244, v67, s[14:15]
	v_cndmask_b32_e64 v68, v244, v68, s[16:17]
	v_cndmask_b32_e64 v69, v244, v69, s[18:19]
	v_cndmask_b32_e64 v70, v244, v70, s[20:21]
	v_cndmask_b32_e64 v71, v244, v71, s[22:23]
	v_cndmask_b32_e64 v72, v244, v72, s[66:67]
	v_cndmask_b32_e64 v73, v244, v73, s[68:69]
	v_cndmask_b32_e64 v74, v244, v74, s[72:73]
	v_cndmask_b32_e64 v75, v244, v75, s[74:75]
	v_cndmask_b32_e64 v76, v244, v76, s[78:79]
	v_cndmask_b32_e64 v77, v244, v77, s[0:1]
	v_cndmask_b32_e64 v78, v244, v78, s[70:71]
	v_cndmask_b32_e64 v79, v244, v79, s[2:3]
	v_add_f32_e32 v48, v48, v216
	v_add_f32_e32 v49, v49, v217
	v_add_f32_e32 v50, v50, v218
	v_add_f32_e32 v51, v51, v219
	ds_read_b128 v[2:5], v236 offset:16384
	ds_read_b128 v[6:9], v236 offset:20480
	ds_read_b128 v[10:13], v237 offset:16384
	ds_read_b128 v[250:253], v237 offset:20480
	v_cndmask_b32_e64 v48, v244, v48, s[90:91]
	v_cndmask_b32_e64 v49, v244, v49, s[94:95]
	v_cndmask_b32_e64 v50, v244, v50, s[44:45]
	v_cndmask_b32_e64 v51, v244, v51, s[84:85]
	v_max3_f32 v245, v64, v65, v66
	v_max3_f32 v245, v245, v67, v68
	v_max3_f32 v245, v245, v69, v70
	v_max3_f32 v245, v245, v71, v72
	v_max3_f32 v245, v245, v73, v74
	v_max3_f32 v245, v245, v75, v76
	v_max3_f32 v245, v245, v77, v78
	v_max3_f32 v245, v245, v79, v48
	v_max3_f32 v245, v245, v49, v50
	v_max_f32_e32 v245, v245, v51
	v_mov_b32_e32 v238, v245
	s_nop 1
	v_permlane32_swap_b32_e32 v245, v238
	v_max_f32_e32 v245, v245, v238
	v_sub_f32_e32 v238, v245, v210
	s_mov_b32 s6, 0x42800000
	v_cmp_ge_f32_e32 vcc, s6, v238
	v_max_f32_e32 v238, v210, v245
	v_sub_f32_e32 v243, v210, v238
	v_mul_f32_e32 v243, 0x3e38aa3b, v243
	v_exp_f32_e32 v243, v243
	s_cmp_eq_u64 vcc, exec
	s_cselect_b64 s[42:43], -1, 0
	v_cndmask_b32_e64 v243, v243, 1.0, s[42:43]
	v_cmp_gt_f32_e32 vcc, 1.0, v243
	s_cbranch_vccz .Lna_norescale_L
	s_and_saveexec_b64 vcc, s[4:5]
	ds_write_b32 v170, v243 offset:32768
	s_or_b64 exec, exec, vcc
	s_waitcnt lgkmcnt(0)
	v_add_u32_e32 v0, s82, v108
	ds_read_b128 v[220:223], v0 offset:32864
	ds_read_b128 v[224:227], v0 offset:32832
	ds_read_b128 v[228:231], v0 offset:32800
	ds_read_b128 v[232:235], v0 offset:32768
	s_waitcnt lgkmcnt(0)
	v_pk_mul_f32 v[28:29], v[28:29], v[220:221]
	v_pk_mul_f32 v[30:31], v[30:31], v[222:223]
	v_pk_mul_f32 v[24:25], v[24:25], v[224:225]
	v_pk_mul_f32 v[26:27], v[26:27], v[226:227]
	v_pk_mul_f32 v[20:21], v[20:21], v[228:229]
	v_pk_mul_f32 v[22:23], v[22:23], v[230:231]
	v_pk_mul_f32 v[16:17], v[16:17], v[232:233]
	v_pk_mul_f32 v[18:19], v[18:19], v[234:235]
	v_pk_mul_f32 v[44:45], v[44:45], v[220:221]
	v_pk_mul_f32 v[46:47], v[46:47], v[222:223]
	v_pk_mul_f32 v[40:41], v[40:41], v[224:225]
	v_pk_mul_f32 v[42:43], v[42:43], v[226:227]
	v_pk_mul_f32 v[36:37], v[36:37], v[228:229]
	v_pk_mul_f32 v[38:39], v[38:39], v[230:231]
	v_pk_mul_f32 v[32:33], v[32:33], v[232:233]
	v_pk_mul_f32 v[34:35], v[34:35], v[234:235]
